# plus: 6-DMA K-loop segments also use SGPR-base LDS-DMA forms (no 64-bit VALU address adds left in the loop)
# speedup vs baseline: 1.0172x; 1.0011x over previous
; #define PG8_STAGE(bufoff, gbase, off, q) do { \
;         __builtin_amdgcn_global_load_lds((const unsigned*)((const char*)(gbase) + (off)), (LAS unsigned*)(lds + (bufoff) + ldsw), 16, 0, 0); \
;         __builtin_amdgcn_global_load_lds((const unsigned*)((const char*)(gbase) + (q) + (off)), (LAS unsigned*)(lds + (bufoff) + ldsw + 8192), 16, 0, 0); } while (0)
; #define PG8_LDA(dst, b, h) do { _Pragma("unroll") for (int m = 0; m < 4; ++m) _Pragma("unroll") for (int k = 0; k < 2; ++k) dst[m][k] = *(const LAS bf16x8*)(lds + PG8_SA(b, h) + aoff + m * 2048 + k * 1024); } while (0)
; #define PG8_LDB(dst, b, h) do { _Pragma("unroll") for (int n = 0; n < 2; ++n) _Pragma("unroll") for (int k = 0; k < 2; ++k) dst[n][k] = *(const LAS bf16x8*)(lds + PG8_SB(b, h) + boff + n * 2048 + k * 1024); } while (0)
; #define PG8_MMA(ai, bj, At, Bt) do { __builtin_amdgcn_s_setprio(1); _Pragma("unroll") for (int m = 0; m < 4; ++m) _Pragma("unroll") for (int n = 0; n < 2; ++n) _Pragma("unroll") for (int k = 0; k < 2; ++k) \
;         acc[ai][bj][m][n] = __builtin_amdgcn_mfma_f32_16x16x32_bf16(Bt[n][k], At[m][k], acc[ai][bj][m][n], 0, 0, 0); __builtin_amdgcn_s_setprio(0); } while (0)
; #define PG8_WAIT_V(n) asm volatile("s_waitcnt vmcnt(" #n ")" ::: "memory")
; #define PG8_WAIT_L(n) asm volatile("s_waitcnt lgkmcnt(" #n ")" ::: "memory")
; #define PG8_BAR __builtin_amdgcn_s_barrier()
; #define PG8_SCHED __builtin_amdgcn_sched_barrier(0)
; template <class Epi, class Sched>
; __device__ __forceinline__ void gemm_phase(LAS unsigned char* lds, const int tid, const Sched& S, const Epi& E) {
;     ...
;             PG8_LDB(B0, 0, 0); PG8_LDB(B1, 0, 1); PG8_SCHED; PG8_LDA(At, 0, 0); PG8_STAGE(PG8_SA(1, 1), a1 + hA, offA, qA);
;             PG8_WAIT_V(8); PG8_WAIT_L(0); PG8_BAR; PG8_MMA(0, 0, At, B0); PG8_MMA(0, 1, At, B1); PG8_BAR; PG8_SCHED;
;             PG8_LDA(At, 0, 1); PG8_STAGE(PG8_SB(0, 0), b2, oB2, qB2); PG8_STAGE(PG8_SB(0, 1), b2 + hB2, oB2, qB2); PG8_STAGE(PG8_SA(0, 0), a2, oA2, qA2);
;             PG8_WAIT_V(8); PG8_WAIT_L(0); PG8_BAR; PG8_MMA(1, 0, At, B0); PG8_MMA(1, 1, At, B1); PG8_BAR; PG8_SCHED;
.LBB0_175:
	s_or_b32 vcc_lo, s17, 1
	s_mov_b32 vcc_hi, s21
	s_lshl_b64 s[10:11], vcc, 7
	s_add_u32 s17, s40, s6
	s_addc_u32 vcc_lo, s41, s7
	s_and_b64 s[6:7], exec, s[62:63]
	s_cselect_b32 vcc_hi, s82, vcc_lo
	s_cselect_b32 vcc_lo, s48, s17
	s_add_i32 s17, 0, 0x10000
	v_add_u32_e32 v133, s17, v147
	s_add_i32 s62, 0, 0x14000
	ds_read_b128 v[140:143], v133
	ds_read_b128 v[150:153], v133 offset:1024
	ds_read_b128 v[154:157], v133 offset:2048
	ds_read_b128 v[158:161], v133 offset:3072
	ds_read_b128 v[186:189], v133 offset:16384
	ds_read_b128 v[190:193], v133 offset:17408
	ds_read_b128 v[194:197], v133 offset:18432
	ds_read_b128 v[198:201], v133 offset:19456
	s_add_u32 s6, s68, s10
	s_addc_u32 s7, s16, s11
	s_add_i32 m0, s54, 0xc000
	ds_read_b128 v[202:205], v184
	ds_read_b128 v[206:209], v184 offset:1024
	ds_read_b128 v[210:213], v184 offset:2048
	ds_read_b128 v[214:217], v184 offset:3072
	ds_read_b128 v[218:221], v184 offset:4096
	ds_read_b128 v[222:225], v184 offset:5120
	ds_read_b128 v[226:229], v184 offset:6144
	ds_read_b128 v[230:233], v184 offset:7168
	global_load_lds_dwordx4 v134, s[6:7]
	s_add_u32 s6, s6, s66
	s_addc_u32 s7, s7, s67
	s_add_i32 m0, s54, 0xe000
	s_nop 0
	global_load_lds_dwordx4 v134, s[6:7]
	s_waitcnt vmcnt(8)
	s_waitcnt lgkmcnt(0)
	s_barrier
	s_setprio 1
	s_waitcnt lgkmcnt(0)
	v_mfma_f32_16x16x32_bf16 v[126:129], v[140:143], v[202:205], v[126:129]
	v_mfma_f32_16x16x32_bf16 v[122:125], v[154:157], v[202:205], v[122:125]
	v_mfma_f32_16x16x32_bf16 v[110:113], v[140:143], v[210:213], v[110:113]
	v_mfma_f32_16x16x32_bf16 v[106:109], v[154:157], v[210:213], v[106:109]
	v_mfma_f32_16x16x32_bf16 v[94:97], v[140:143], v[218:221], v[94:97]
	v_mfma_f32_16x16x32_bf16 v[90:93], v[154:157], v[218:221], v[90:93]
	v_mfma_f32_16x16x32_bf16 v[78:81], v[140:143], v[226:229], v[78:81]
	v_mfma_f32_16x16x32_bf16 v[74:77], v[154:157], v[226:229], v[74:77]
	v_mfma_f32_16x16x32_bf16 v[126:129], v[150:153], v[206:209], v[126:129]
	v_mfma_f32_16x16x32_bf16 v[122:125], v[158:161], v[206:209], v[122:125]
	v_mfma_f32_16x16x32_bf16 v[110:113], v[150:153], v[214:217], v[110:113]
	v_mfma_f32_16x16x32_bf16 v[106:109], v[158:161], v[214:217], v[106:109]
	v_mfma_f32_16x16x32_bf16 v[94:97], v[150:153], v[222:225], v[94:97]
	v_mfma_f32_16x16x32_bf16 v[90:93], v[158:161], v[222:225], v[90:93]
	v_mfma_f32_16x16x32_bf16 v[78:81], v[150:153], v[230:233], v[78:81]
	v_mfma_f32_16x16x32_bf16 v[74:77], v[158:161], v[230:233], v[74:77]
	s_setprio 0
	s_setprio 1
	v_mfma_f32_16x16x32_bf16 v[118:121], v[186:189], v[202:205], v[118:121]
	v_mfma_f32_16x16x32_bf16 v[114:117], v[194:197], v[202:205], v[114:117]
	v_mfma_f32_16x16x32_bf16 v[102:105], v[186:189], v[210:213], v[102:105]
	v_mfma_f32_16x16x32_bf16 v[98:101], v[194:197], v[210:213], v[98:101]
	v_mfma_f32_16x16x32_bf16 v[86:89], v[186:189], v[218:221], v[86:89]
	v_mfma_f32_16x16x32_bf16 v[82:85], v[194:197], v[218:221], v[82:85]
	v_mfma_f32_16x16x32_bf16 v[70:73], v[186:189], v[226:229], v[70:73]
	v_mfma_f32_16x16x32_bf16 v[66:69], v[194:197], v[226:229], v[66:69]
	v_mfma_f32_16x16x32_bf16 v[118:121], v[190:193], v[206:209], v[118:121]
	v_mfma_f32_16x16x32_bf16 v[114:117], v[198:201], v[206:209], v[114:117]
	v_mfma_f32_16x16x32_bf16 v[102:105], v[190:193], v[214:217], v[102:105]
	v_mfma_f32_16x16x32_bf16 v[98:101], v[198:201], v[214:217], v[98:101]
	v_mfma_f32_16x16x32_bf16 v[86:89], v[190:193], v[222:225], v[86:89]
	v_mfma_f32_16x16x32_bf16 v[82:85], v[198:201], v[222:225], v[82:85]
	v_mfma_f32_16x16x32_bf16 v[70:73], v[190:193], v[230:233], v[70:73]
	v_mfma_f32_16x16x32_bf16 v[66:69], v[198:201], v[230:233], v[66:69]
	s_setprio 0
	s_barrier
	s_add_i32 s10, s17, s47
	s_ashr_i32 s11, s73, 31
	s_mov_b32 m0, s10
	s_add_u32 s6, s28, s73
	ds_read_b128 v[202:205], v184 offset:16384
	ds_read_b128 v[206:209], v184 offset:17408
	ds_read_b128 v[210:213], v184 offset:18432
	ds_read_b128 v[214:217], v184 offset:19456
	ds_read_b128 v[218:221], v184 offset:20480
	ds_read_b128 v[222:225], v184 offset:21504
	ds_read_b128 v[226:229], v184 offset:22528
	ds_read_b128 v[230:233], v184 offset:23552
	global_load_lds_dwordx4 v0, s[28:29]
	s_addc_u32 s7, s29, s11
	s_add_i32 m0, s10, 0x2000
	s_nop 0
	global_load_lds_dwordx4 v0, s[6:7]
	s_ashr_i32 s7, s19, 31
	s_add_u32 s6, s28, s19
	s_addc_u32 s7, s29, s7
	s_add_i32 s10, s62, s47
	s_mov_b32 m0, s10
	s_nop 0
	global_load_lds_dwordx4 v0, s[6:7]
	s_add_u32 s6, s6, s73
	s_addc_u32 s7, s7, s11
	s_add_i32 m0, s10, 0x2000
	s_nop 0
	global_load_lds_dwordx4 v0, s[6:7]
	s_add_u32 s6, vcc_lo, s64
	s_mov_b32 m0, s54
	s_addc_u32 s7, vcc_hi, s65
	global_load_lds_dwordx4 v136, vcc
	s_mov_b32 m0, s55
	s_nop 0
	global_load_lds_dwordx4 v136, s[6:7]
	s_waitcnt vmcnt(8)
	s_waitcnt lgkmcnt(0)
	s_barrier
; #define PG8_STAGE(bufoff, gbase, off, q) do { \
;         __builtin_amdgcn_global_load_lds((const unsigned*)((const char*)(gbase) + (off)), (LAS unsigned*)(lds + (bufoff) + ldsw), 16, 0, 0); \
;         __builtin_amdgcn_global_load_lds((const unsigned*)((const char*)(gbase) + (q) + (off)), (LAS unsigned*)(lds + (bufoff) + ldsw + 8192), 16, 0, 0); } while (0)
; #define PG8_LDA(dst, b, h) do { _Pragma("unroll") for (int m = 0; m < 4; ++m) _Pragma("unroll") for (int k = 0; k < 2; ++k) dst[m][k] = *(const LAS bf16x8*)(lds + PG8_SA(b, h) + aoff + m * 2048 + k * 1024); } while (0)
; #define PG8_LDB(dst, b, h) do { _Pragma("unroll") for (int n = 0; n < 2; ++n) _Pragma("unroll") for (int k = 0; k < 2; ++k) dst[n][k] = *(const LAS bf16x8*)(lds + PG8_SB(b, h) + boff + n * 2048 + k * 1024); } while (0)
; #define PG8_MMA(ai, bj, At, Bt) do { __builtin_amdgcn_s_setprio(1); _Pragma("unroll") for (int m = 0; m < 4; ++m) _Pragma("unroll") for (int n = 0; n < 2; ++n) _Pragma("unroll") for (int k = 0; k < 2; ++k) \
;         acc[ai][bj][m][n] = __builtin_amdgcn_mfma_f32_16x16x32_bf16(Bt[n][k], At[m][k], acc[ai][bj][m][n], 0, 0, 0); __builtin_amdgcn_s_setprio(0); } while (0)
; #define PG8_WAIT_V(n) asm volatile("s_waitcnt vmcnt(" #n ")" ::: "memory")
; #define PG8_WAIT_L(n) asm volatile("s_waitcnt lgkmcnt(" #n ")" ::: "memory")
; #define PG8_BAR __builtin_amdgcn_s_barrier()
; #define PG8_SCHED __builtin_amdgcn_sched_barrier(0)
; template <class Epi, class Sched>
; __device__ __forceinline__ void gemm_phase(LAS unsigned char* lds, const int tid, const Sched& S, const Epi& E) {
;     ...
;             PG8_WAIT_V(8); PG8_WAIT_L(0); PG8_BAR; PG8_MMA(1, 0, At, B0); PG8_MMA(1, 1, At, B1); PG8_BAR; PG8_SCHED;
;             PG8_LDB(B0, 1, 0); PG8_LDB(B1, 1, 1); PG8_SCHED; PG8_LDA(At, 1, 0); PG8_STAGE(PG8_SA(0, 1), a2 + hA2, oA2, qA2);
;             PG8_WAIT_V(8); PG8_WAIT_L(0); PG8_BAR; PG8_MMA(0, 0, At, B0); PG8_MMA(0, 1, At, B1); PG8_BAR; PG8_SCHED;
	s_setprio 1
	s_waitcnt lgkmcnt(0)
	v_mfma_f32_16x16x32_bf16 v[62:65], v[140:143], v[202:205], v[62:65]
	v_mfma_f32_16x16x32_bf16 v[58:61], v[154:157], v[202:205], v[58:61]
	v_mfma_f32_16x16x32_bf16 v[46:49], v[140:143], v[210:213], v[46:49]
	v_mfma_f32_16x16x32_bf16 v[42:45], v[154:157], v[210:213], v[42:45]
	v_mfma_f32_16x16x32_bf16 v[30:33], v[140:143], v[218:221], v[30:33]
	v_mfma_f32_16x16x32_bf16 v[26:29], v[154:157], v[218:221], v[26:29]
	v_mfma_f32_16x16x32_bf16 v[14:17], v[140:143], v[226:229], v[14:17]
	v_mfma_f32_16x16x32_bf16 v[10:13], v[154:157], v[226:229], v[10:13]
	v_mfma_f32_16x16x32_bf16 v[62:65], v[150:153], v[206:209], v[62:65]
	v_mfma_f32_16x16x32_bf16 v[58:61], v[158:161], v[206:209], v[58:61]
	v_mfma_f32_16x16x32_bf16 v[46:49], v[150:153], v[214:217], v[46:49]
	v_mfma_f32_16x16x32_bf16 v[42:45], v[158:161], v[214:217], v[42:45]
	v_mfma_f32_16x16x32_bf16 v[30:33], v[150:153], v[222:225], v[30:33]
	v_mfma_f32_16x16x32_bf16 v[26:29], v[158:161], v[222:225], v[26:29]
	v_mfma_f32_16x16x32_bf16 v[14:17], v[150:153], v[230:233], v[14:17]
	v_mfma_f32_16x16x32_bf16 v[10:13], v[158:161], v[230:233], v[10:13]
	s_setprio 0
	s_setprio 1
	v_mfma_f32_16x16x32_bf16 v[54:57], v[186:189], v[202:205], v[54:57]
	v_mfma_f32_16x16x32_bf16 v[50:53], v[194:197], v[202:205], v[50:53]
	v_mfma_f32_16x16x32_bf16 v[38:41], v[186:189], v[210:213], v[38:41]
	v_mfma_f32_16x16x32_bf16 v[34:37], v[194:197], v[210:213], v[34:37]
	v_mfma_f32_16x16x32_bf16 v[22:25], v[186:189], v[218:221], v[22:25]
	v_mfma_f32_16x16x32_bf16 v[18:21], v[194:197], v[218:221], v[18:21]
	v_mfma_f32_16x16x32_bf16 v[6:9], v[186:189], v[226:229], v[6:9]
	v_mfma_f32_16x16x32_bf16 v[2:5], v[194:197], v[226:229], v[2:5]
	v_mfma_f32_16x16x32_bf16 v[54:57], v[190:193], v[206:209], v[54:57]
	v_mfma_f32_16x16x32_bf16 v[50:53], v[198:201], v[206:209], v[50:53]
	v_mfma_f32_16x16x32_bf16 v[38:41], v[190:193], v[214:217], v[38:41]
	v_mfma_f32_16x16x32_bf16 v[34:37], v[198:201], v[214:217], v[34:37]
	v_mfma_f32_16x16x32_bf16 v[22:25], v[190:193], v[222:225], v[22:25]
	v_mfma_f32_16x16x32_bf16 v[18:21], v[198:201], v[222:225], v[18:21]
	v_mfma_f32_16x16x32_bf16 v[6:9], v[190:193], v[230:233], v[6:9]
	v_mfma_f32_16x16x32_bf16 v[2:5], v[198:201], v[230:233], v[2:5]
	s_setprio 0
	s_barrier
	s_add_i32 s10, 0, 0x18000
	s_add_i32 s11, 0, 0x1c000
	ds_read_b128 v[140:143], v133 offset:32768
	ds_read_b128 v[150:153], v133 offset:33792
	ds_read_b128 v[154:157], v133 offset:34816
	ds_read_b128 v[158:161], v133 offset:35840
	ds_read_b128 v[186:189], v133 offset:49152
	ds_read_b128 v[190:193], v133 offset:50176
	ds_read_b128 v[194:197], v133 offset:51200
	ds_read_b128 v[198:201], v133 offset:52224
	s_add_u32 s6, vcc_lo, s58
	s_addc_u32 s7, vcc_hi, s59
	s_mov_b32 m0, s91
	ds_read_b128 v[202:205], v184 offset:32768
	ds_read_b128 v[206:209], v184 offset:33792
	ds_read_b128 v[210:213], v184 offset:34816
	ds_read_b128 v[214:217], v184 offset:35840
	ds_read_b128 v[218:221], v184 offset:36864
	ds_read_b128 v[222:225], v184 offset:37888
	ds_read_b128 v[226:229], v184 offset:38912
	ds_read_b128 v[230:233], v184 offset:39936
	global_load_lds_dwordx4 v136, s[6:7]
	s_add_u32 s6, s6, s64
	s_addc_u32 s7, s7, s65
	s_mov_b32 m0, s93
	s_nop 0
	global_load_lds_dwordx4 v136, s[6:7]
	s_waitcnt vmcnt(8)
	s_waitcnt lgkmcnt(0)
	s_barrier
	s_setprio 1
	s_waitcnt lgkmcnt(0)
	v_mfma_f32_16x16x32_bf16 v[126:129], v[140:143], v[202:205], v[126:129]
	v_mfma_f32_16x16x32_bf16 v[122:125], v[154:157], v[202:205], v[122:125]
	v_mfma_f32_16x16x32_bf16 v[110:113], v[140:143], v[210:213], v[110:113]
	v_mfma_f32_16x16x32_bf16 v[106:109], v[154:157], v[210:213], v[106:109]
	v_mfma_f32_16x16x32_bf16 v[94:97], v[140:143], v[218:221], v[94:97]
	v_mfma_f32_16x16x32_bf16 v[90:93], v[154:157], v[218:221], v[90:93]
	v_mfma_f32_16x16x32_bf16 v[78:81], v[140:143], v[226:229], v[78:81]
	v_mfma_f32_16x16x32_bf16 v[74:77], v[154:157], v[226:229], v[74:77]
	v_mfma_f32_16x16x32_bf16 v[126:129], v[150:153], v[206:209], v[126:129]
	v_mfma_f32_16x16x32_bf16 v[122:125], v[158:161], v[206:209], v[122:125]
	v_mfma_f32_16x16x32_bf16 v[110:113], v[150:153], v[214:217], v[110:113]
	v_mfma_f32_16x16x32_bf16 v[106:109], v[158:161], v[214:217], v[106:109]
	v_mfma_f32_16x16x32_bf16 v[94:97], v[150:153], v[222:225], v[94:97]
	v_mfma_f32_16x16x32_bf16 v[90:93], v[158:161], v[222:225], v[90:93]
	v_mfma_f32_16x16x32_bf16 v[78:81], v[150:153], v[230:233], v[78:81]
	v_mfma_f32_16x16x32_bf16 v[74:77], v[158:161], v[230:233], v[74:77]
	s_setprio 0
	s_setprio 1
	v_mfma_f32_16x16x32_bf16 v[118:121], v[186:189], v[202:205], v[118:121]
	v_mfma_f32_16x16x32_bf16 v[114:117], v[194:197], v[202:205], v[114:117]
	v_mfma_f32_16x16x32_bf16 v[102:105], v[186:189], v[210:213], v[102:105]
	v_mfma_f32_16x16x32_bf16 v[98:101], v[194:197], v[210:213], v[98:101]
	v_mfma_f32_16x16x32_bf16 v[86:89], v[186:189], v[218:221], v[86:89]
	v_mfma_f32_16x16x32_bf16 v[82:85], v[194:197], v[218:221], v[82:85]
	v_mfma_f32_16x16x32_bf16 v[70:73], v[186:189], v[226:229], v[70:73]
	v_mfma_f32_16x16x32_bf16 v[66:69], v[194:197], v[226:229], v[66:69]
	v_mfma_f32_16x16x32_bf16 v[118:121], v[190:193], v[206:209], v[118:121]
	v_mfma_f32_16x16x32_bf16 v[114:117], v[198:201], v[206:209], v[114:117]
	v_mfma_f32_16x16x32_bf16 v[102:105], v[190:193], v[214:217], v[102:105]
	v_mfma_f32_16x16x32_bf16 v[98:101], v[198:201], v[214:217], v[98:101]
	v_mfma_f32_16x16x32_bf16 v[86:89], v[190:193], v[222:225], v[86:89]
	v_mfma_f32_16x16x32_bf16 v[82:85], v[198:201], v[222:225], v[82:85]
	v_mfma_f32_16x16x32_bf16 v[70:73], v[190:193], v[230:233], v[70:73]
	v_mfma_f32_16x16x32_bf16 v[66:69], v[198:201], v[230:233], v[66:69]
	s_setprio 0
	s_barrier
; #define PG8_STAGE(bufoff, gbase, off, q) do { \
;         __builtin_amdgcn_global_load_lds((const unsigned*)((const char*)(gbase) + (off)), (LAS unsigned*)(lds + (bufoff) + ldsw), 16, 0, 0); \
;         __builtin_amdgcn_global_load_lds((const unsigned*)((const char*)(gbase) + (q) + (off)), (LAS unsigned*)(lds + (bufoff) + ldsw + 8192), 16, 0, 0); } while (0)
; #define PG8_LDA(dst, b, h) do { _Pragma("unroll") for (int m = 0; m < 4; ++m) _Pragma("unroll") for (int k = 0; k < 2; ++k) dst[m][k] = *(const LAS bf16x8*)(lds + PG8_SA(b, h) + aoff + m * 2048 + k * 1024); } while (0)
; #define PG8_MMA(ai, bj, At, Bt) do { __builtin_amdgcn_s_setprio(1); _Pragma("unroll") for (int m = 0; m < 4; ++m) _Pragma("unroll") for (int n = 0; n < 2; ++n) _Pragma("unroll") for (int k = 0; k < 2; ++k) \
;         acc[ai][bj][m][n] = __builtin_amdgcn_mfma_f32_16x16x32_bf16(Bt[n][k], At[m][k], acc[ai][bj][m][n], 0, 0, 0); __builtin_amdgcn_s_setprio(0); } while (0)
; #define PG8_WAIT_V(n) asm volatile("s_waitcnt vmcnt(" #n ")" ::: "memory")
; #define PG8_WAIT_L(n) asm volatile("s_waitcnt lgkmcnt(" #n ")" ::: "memory")
; #define PG8_BAR __builtin_amdgcn_s_barrier()
; #define PG8_SCHED __builtin_amdgcn_sched_barrier(0)
; template <class Epi, class Sched>
; __device__ __forceinline__ void gemm_phase(LAS unsigned char* lds, const int tid, const Sched& S, const Epi& E) {
;     ...
;             PG8_LDA(At, 1, 1); PG8_STAGE(PG8_SB(1, 0), b3, oB2, qB2); PG8_STAGE(PG8_SB(1, 1), b3 + hB2, oB2, qB2); PG8_STAGE(PG8_SA(1, 0), a3, oA2, qA2);
;             PG8_WAIT_V(8); PG8_WAIT_L(0); PG8_BAR; PG8_MMA(1, 0, At, B0); PG8_MMA(1, 1, At, B1); PG8_BAR; PG8_SCHED;
;         }
	s_add_i32 s6, s10, s47
	s_add_i32 m0, s6, 0xffffff80
	ds_read_b128 v[202:205], v184 offset:49152
	ds_read_b128 v[206:209], v184 offset:50176
	ds_read_b128 v[210:213], v184 offset:51200
	ds_read_b128 v[214:217], v184 offset:52224
	ds_read_b128 v[218:221], v184 offset:53248
	ds_read_b128 v[222:225], v184 offset:54272
	ds_read_b128 v[226:229], v184 offset:55296
	ds_read_b128 v[230:233], v184 offset:56320
	global_load_lds_dwordx4 v0, s[28:29] offset:128
	s_add_i32 m0, s6, 0x1f80
	s_add_i32 s6, s11, s47
	s_ashr_i32 s100, s73, 31
	s_add_u32 s98, s28, s73
	s_addc_u32 s99, s29, s100
	global_load_lds_dwordx4 v0, s[98:99] offset:128
	s_add_i32 m0, s6, 0xffffff80
	s_nop 0
	s_ashr_i32 s101, s19, 31
	s_add_u32 s98, s28, s19
	s_addc_u32 s99, s29, s101
	global_load_lds_dwordx4 v0, s[98:99] offset:128
	s_add_i32 m0, s6, 0x1f80
	s_nop 0
	s_add_u32 s98, s98, s73
	s_addc_u32 s99, s99, s100
	global_load_lds_dwordx4 v0, s[98:99] offset:128
	s_add_i32 m0, s77, 0xffffff80
	s_nop 0
	global_load_lds_dwordx4 v136, vcc offset:128
	s_add_i32 m0, s88, 0xffffff80
	s_nop 0
	s_add_u32 s98, vcc_lo, s64
	s_addc_u32 s99, vcc_hi, s65
	global_load_lds_dwordx4 v136, s[98:99] offset:128
	s_waitcnt vmcnt(8)
	s_waitcnt lgkmcnt(0)
	s_barrier
	s_setprio 1
	s_waitcnt lgkmcnt(0)
	v_mfma_f32_16x16x32_bf16 v[62:65], v[140:143], v[202:205], v[62:65]
	v_mfma_f32_16x16x32_bf16 v[58:61], v[154:157], v[202:205], v[58:61]
	v_mfma_f32_16x16x32_bf16 v[46:49], v[140:143], v[210:213], v[46:49]
	v_mfma_f32_16x16x32_bf16 v[42:45], v[154:157], v[210:213], v[42:45]
	v_mfma_f32_16x16x32_bf16 v[30:33], v[140:143], v[218:221], v[30:33]
	v_mfma_f32_16x16x32_bf16 v[26:29], v[154:157], v[218:221], v[26:29]
	v_mfma_f32_16x16x32_bf16 v[14:17], v[140:143], v[226:229], v[14:17]
	v_mfma_f32_16x16x32_bf16 v[10:13], v[154:157], v[226:229], v[10:13]
	v_mfma_f32_16x16x32_bf16 v[62:65], v[150:153], v[206:209], v[62:65]
	v_mfma_f32_16x16x32_bf16 v[58:61], v[158:161], v[206:209], v[58:61]
	v_mfma_f32_16x16x32_bf16 v[46:49], v[150:153], v[214:217], v[46:49]
	v_mfma_f32_16x16x32_bf16 v[42:45], v[158:161], v[214:217], v[42:45]
	v_mfma_f32_16x16x32_bf16 v[30:33], v[150:153], v[222:225], v[30:33]
	v_mfma_f32_16x16x32_bf16 v[26:29], v[158:161], v[222:225], v[26:29]
	v_mfma_f32_16x16x32_bf16 v[14:17], v[150:153], v[230:233], v[14:17]
	v_mfma_f32_16x16x32_bf16 v[10:13], v[158:161], v[230:233], v[10:13]
	s_setprio 0
	s_setprio 1
	v_mfma_f32_16x16x32_bf16 v[54:57], v[186:189], v[202:205], v[54:57]
	v_mfma_f32_16x16x32_bf16 v[50:53], v[194:197], v[202:205], v[50:53]
	v_mfma_f32_16x16x32_bf16 v[38:41], v[186:189], v[210:213], v[38:41]
	v_mfma_f32_16x16x32_bf16 v[34:37], v[194:197], v[210:213], v[34:37]
	v_mfma_f32_16x16x32_bf16 v[22:25], v[186:189], v[218:221], v[22:25]
	v_mfma_f32_16x16x32_bf16 v[18:21], v[194:197], v[218:221], v[18:21]
	v_mfma_f32_16x16x32_bf16 v[6:9], v[186:189], v[226:229], v[6:9]
	v_mfma_f32_16x16x32_bf16 v[2:5], v[194:197], v[226:229], v[2:5]
	v_mfma_f32_16x16x32_bf16 v[54:57], v[190:193], v[206:209], v[54:57]
	v_mfma_f32_16x16x32_bf16 v[50:53], v[198:201], v[206:209], v[50:53]
	v_mfma_f32_16x16x32_bf16 v[38:41], v[190:193], v[214:217], v[38:41]
	v_mfma_f32_16x16x32_bf16 v[34:37], v[198:201], v[214:217], v[34:37]
	v_mfma_f32_16x16x32_bf16 v[22:25], v[190:193], v[222:225], v[22:25]
	v_mfma_f32_16x16x32_bf16 v[18:21], v[198:201], v[222:225], v[18:21]
	v_mfma_f32_16x16x32_bf16 v[6:9], v[190:193], v[230:233], v[6:9]
	v_mfma_f32_16x16x32_bf16 v[2:5], v[198:201], v[230:233], v[2:5]
	s_setprio 0
	s_barrier
	s_cmp_ge_i32 s20, s37
	s_cbranch_scc1 .LBB0_177
	s_mov_b32 s17, s20
	s_branch .LBB0_173

; #define PG8_STAGE(bufoff, gbase, off, q) do { \
;         __builtin_amdgcn_global_load_lds((const unsigned*)((const char*)(gbase) + (off)), (LAS unsigned*)(lds + (bufoff) + ldsw), 16, 0, 0); \
;         __builtin_amdgcn_global_load_lds((const unsigned*)((const char*)(gbase) + (q) + (off)), (LAS unsigned*)(lds + (bufoff) + ldsw + 8192), 16, 0, 0); } while (0)
; #define PG8_LDA(dst, b, h) do { _Pragma("unroll") for (int m = 0; m < 4; ++m) _Pragma("unroll") for (int k = 0; k < 2; ++k) dst[m][k] = *(const LAS bf16x8*)(lds + PG8_SA(b, h) + aoff + m * 2048 + k * 1024); } while (0)
; #define PG8_LDB(dst, b, h) do { _Pragma("unroll") for (int n = 0; n < 2; ++n) _Pragma("unroll") for (int k = 0; k < 2; ++k) dst[n][k] = *(const LAS bf16x8*)(lds + PG8_SB(b, h) + boff + n * 2048 + k * 1024); } while (0)
; #define PG8_MMA(ai, bj, At, Bt) do { __builtin_amdgcn_s_setprio(1); _Pragma("unroll") for (int m = 0; m < 4; ++m) _Pragma("unroll") for (int n = 0; n < 2; ++n) _Pragma("unroll") for (int k = 0; k < 2; ++k) \
;         acc[ai][bj][m][n] = __builtin_amdgcn_mfma_f32_16x16x32_bf16(Bt[n][k], At[m][k], acc[ai][bj][m][n], 0, 0, 0); __builtin_amdgcn_s_setprio(0); } while (0)
; #define PG8_WAIT_V(n) asm volatile("s_waitcnt vmcnt(" #n ")" ::: "memory")
; #define PG8_WAIT_L(n) asm volatile("s_waitcnt lgkmcnt(" #n ")" ::: "memory")
; #define PG8_BAR __builtin_amdgcn_s_barrier()
; #define PG8_SCHED __builtin_amdgcn_sched_barrier(0)
; template <class Epi, class Sched>
; __device__ __forceinline__ void gemm_phase(LAS unsigned char* lds, const int tid, const Sched& S, const Epi& E) {
;     ...
;             PG8_LDB(B0, 0, 0); PG8_LDB(B1, 0, 1); PG8_SCHED; PG8_LDA(At, 0, 0); PG8_STAGE(PG8_SA(1, 1), a1 + hA, offA, qA);
;             PG8_WAIT_V(8); PG8_WAIT_L(0); PG8_BAR; PG8_MMA(0, 0, At, B0); PG8_MMA(0, 1, At, B1); PG8_BAR; PG8_SCHED;
;             PG8_LDA(At, 0, 1); PG8_STAGE(PG8_SB(0, 0), b2, oB2, qB2); PG8_STAGE(PG8_SB(0, 1), b2 + hB2, oB2, qB2); PG8_STAGE(PG8_SA(0, 0), a2, oA2, qA2);
;             PG8_WAIT_V(8); PG8_WAIT_L(0); PG8_BAR; PG8_MMA(1, 0, At, B0); PG8_MMA(1, 1, At, B1); PG8_BAR; PG8_SCHED;
.Lk0a_175:
	s_or_b32 vcc_lo, s17, 1
	s_mov_b32 vcc_hi, s21
	s_lshl_b64 s[10:11], vcc, 7
	s_add_u32 s17, s40, s6
	s_addc_u32 vcc_lo, s41, s7
	s_and_b64 s[6:7], exec, s[62:63]
	s_cselect_b32 vcc_hi, s82, vcc_lo
	s_cselect_b32 vcc_lo, s48, s17
	s_add_i32 s17, 0, 0x10000
	v_add_u32_e32 v133, s17, v147
	s_add_i32 s62, 0, 0x14000
	ds_read_b128 v[140:143], v133
	ds_read_b128 v[150:153], v133 offset:1024
	ds_read_b128 v[154:157], v133 offset:2048
	ds_read_b128 v[158:161], v133 offset:3072
	ds_read_b128 v[186:189], v133 offset:16384
	ds_read_b128 v[190:193], v133 offset:17408
	ds_read_b128 v[194:197], v133 offset:18432
	ds_read_b128 v[198:201], v133 offset:19456
	s_add_u32 s6, s68, s10
	s_addc_u32 s7, s16, s11
	s_add_i32 m0, s54, 0xc000
	ds_read_b128 v[202:205], v184
	ds_read_b128 v[206:209], v184 offset:1024
	ds_read_b128 v[210:213], v184 offset:2048
	ds_read_b128 v[214:217], v184 offset:3072
	ds_read_b128 v[218:221], v184 offset:4096
	ds_read_b128 v[222:225], v184 offset:5120
	ds_read_b128 v[226:229], v184 offset:6144
	ds_read_b128 v[230:233], v184 offset:7168
	global_load_lds_dwordx4 v134, s[6:7]
	s_add_u32 s6, s6, s66
	s_addc_u32 s7, s7, s67
	s_add_i32 m0, s54, 0xe000
	s_nop 0
	global_load_lds_dwordx4 v134, s[6:7]
	s_waitcnt vmcnt(16)
	s_waitcnt lgkmcnt(0)
	s_barrier
	s_setprio 1
	s_waitcnt lgkmcnt(0)
	v_mfma_f32_16x16x32_bf16 v[126:129], v[140:143], v[202:205], v[126:129]
	v_mfma_f32_16x16x32_bf16 v[122:125], v[154:157], v[202:205], v[122:125]
	v_mfma_f32_16x16x32_bf16 v[110:113], v[140:143], v[210:213], v[110:113]
	v_mfma_f32_16x16x32_bf16 v[106:109], v[154:157], v[210:213], v[106:109]
	v_mfma_f32_16x16x32_bf16 v[94:97], v[140:143], v[218:221], v[94:97]
	v_mfma_f32_16x16x32_bf16 v[90:93], v[154:157], v[218:221], v[90:93]
	v_mfma_f32_16x16x32_bf16 v[78:81], v[140:143], v[226:229], v[78:81]
	v_mfma_f32_16x16x32_bf16 v[74:77], v[154:157], v[226:229], v[74:77]
	v_mfma_f32_16x16x32_bf16 v[126:129], v[150:153], v[206:209], v[126:129]
	v_mfma_f32_16x16x32_bf16 v[122:125], v[158:161], v[206:209], v[122:125]
	v_mfma_f32_16x16x32_bf16 v[110:113], v[150:153], v[214:217], v[110:113]
	v_mfma_f32_16x16x32_bf16 v[106:109], v[158:161], v[214:217], v[106:109]
	v_mfma_f32_16x16x32_bf16 v[94:97], v[150:153], v[222:225], v[94:97]
	v_mfma_f32_16x16x32_bf16 v[90:93], v[158:161], v[222:225], v[90:93]
	v_mfma_f32_16x16x32_bf16 v[78:81], v[150:153], v[230:233], v[78:81]
	v_mfma_f32_16x16x32_bf16 v[74:77], v[158:161], v[230:233], v[74:77]
	s_setprio 0
	s_setprio 1
	v_mfma_f32_16x16x32_bf16 v[118:121], v[186:189], v[202:205], v[118:121]
	v_mfma_f32_16x16x32_bf16 v[114:117], v[194:197], v[202:205], v[114:117]
	v_mfma_f32_16x16x32_bf16 v[102:105], v[186:189], v[210:213], v[102:105]
	v_mfma_f32_16x16x32_bf16 v[98:101], v[194:197], v[210:213], v[98:101]
	v_mfma_f32_16x16x32_bf16 v[86:89], v[186:189], v[218:221], v[86:89]
	v_mfma_f32_16x16x32_bf16 v[82:85], v[194:197], v[218:221], v[82:85]
	v_mfma_f32_16x16x32_bf16 v[70:73], v[186:189], v[226:229], v[70:73]
	v_mfma_f32_16x16x32_bf16 v[66:69], v[194:197], v[226:229], v[66:69]
	v_mfma_f32_16x16x32_bf16 v[118:121], v[190:193], v[206:209], v[118:121]
	v_mfma_f32_16x16x32_bf16 v[114:117], v[198:201], v[206:209], v[114:117]
	v_mfma_f32_16x16x32_bf16 v[102:105], v[190:193], v[214:217], v[102:105]
	v_mfma_f32_16x16x32_bf16 v[98:101], v[198:201], v[214:217], v[98:101]
	v_mfma_f32_16x16x32_bf16 v[86:89], v[190:193], v[222:225], v[86:89]
	v_mfma_f32_16x16x32_bf16 v[82:85], v[198:201], v[222:225], v[82:85]
	v_mfma_f32_16x16x32_bf16 v[70:73], v[190:193], v[230:233], v[70:73]
	v_mfma_f32_16x16x32_bf16 v[66:69], v[198:201], v[230:233], v[66:69]
	s_setprio 0
	s_barrier
	s_add_i32 s10, s17, s47
	s_ashr_i32 s11, s73, 31
	s_mov_b32 m0, s10
	s_add_u32 s6, s28, s73
	ds_read_b128 v[202:205], v184 offset:16384
	ds_read_b128 v[206:209], v184 offset:17408
	ds_read_b128 v[210:213], v184 offset:18432
	ds_read_b128 v[214:217], v184 offset:19456
	ds_read_b128 v[218:221], v184 offset:20480
	ds_read_b128 v[222:225], v184 offset:21504
	ds_read_b128 v[226:229], v184 offset:22528
	ds_read_b128 v[230:233], v184 offset:23552
	global_load_lds_dwordx4 v0, s[28:29]
	s_addc_u32 s7, s29, s11
	s_add_i32 m0, s10, 0x2000
	s_nop 0
	global_load_lds_dwordx4 v0, s[6:7]
	s_ashr_i32 s7, s19, 31
	s_add_u32 s6, s28, s19
	s_addc_u32 s7, s29, s7
	s_add_i32 s10, s62, s47
	s_mov_b32 m0, s10
	s_nop 0
	global_load_lds_dwordx4 v0, s[6:7]
	s_add_u32 s6, s6, s73
	s_addc_u32 s7, s7, s11
	s_add_i32 m0, s10, 0x2000
	s_nop 0
	global_load_lds_dwordx4 v0, s[6:7]
	s_add_u32 s6, vcc_lo, s64
	s_mov_b32 m0, s54
	s_addc_u32 s7, vcc_hi, s65
	global_load_lds_dwordx4 v136, vcc
	s_mov_b32 m0, s55
	s_nop 0
	global_load_lds_dwordx4 v136, s[6:7]
	s_waitcnt vmcnt(16)
	s_waitcnt lgkmcnt(0)
	s_barrier
; #define PG8_STAGE(bufoff, gbase, off, q) do { \
;         __builtin_amdgcn_global_load_lds((const unsigned*)((const char*)(gbase) + (off)), (LAS unsigned*)(lds + (bufoff) + ldsw), 16, 0, 0); \
;         __builtin_amdgcn_global_load_lds((const unsigned*)((const char*)(gbase) + (q) + (off)), (LAS unsigned*)(lds + (bufoff) + ldsw + 8192), 16, 0, 0); } while (0)
; #define PG8_LDA(dst, b, h) do { _Pragma("unroll") for (int m = 0; m < 4; ++m) _Pragma("unroll") for (int k = 0; k < 2; ++k) dst[m][k] = *(const LAS bf16x8*)(lds + PG8_SA(b, h) + aoff + m * 2048 + k * 1024); } while (0)
; #define PG8_LDB(dst, b, h) do { _Pragma("unroll") for (int n = 0; n < 2; ++n) _Pragma("unroll") for (int k = 0; k < 2; ++k) dst[n][k] = *(const LAS bf16x8*)(lds + PG8_SB(b, h) + boff + n * 2048 + k * 1024); } while (0)
; #define PG8_MMA(ai, bj, At, Bt) do { __builtin_amdgcn_s_setprio(1); _Pragma("unroll") for (int m = 0; m < 4; ++m) _Pragma("unroll") for (int n = 0; n < 2; ++n) _Pragma("unroll") for (int k = 0; k < 2; ++k) \
;         acc[ai][bj][m][n] = __builtin_amdgcn_mfma_f32_16x16x32_bf16(Bt[n][k], At[m][k], acc[ai][bj][m][n], 0, 0, 0); __builtin_amdgcn_s_setprio(0); } while (0)
; #define PG8_WAIT_V(n) asm volatile("s_waitcnt vmcnt(" #n ")" ::: "memory")
; #define PG8_WAIT_L(n) asm volatile("s_waitcnt lgkmcnt(" #n ")" ::: "memory")
; #define PG8_BAR __builtin_amdgcn_s_barrier()
; #define PG8_SCHED __builtin_amdgcn_sched_barrier(0)
; template <class Epi, class Sched>
; __device__ __forceinline__ void gemm_phase(LAS unsigned char* lds, const int tid, const Sched& S, const Epi& E) {
;     ...
;             PG8_WAIT_V(8); PG8_WAIT_L(0); PG8_BAR; PG8_MMA(1, 0, At, B0); PG8_MMA(1, 1, At, B1); PG8_BAR; PG8_SCHED;
;             PG8_LDB(B0, 1, 0); PG8_LDB(B1, 1, 1); PG8_SCHED; PG8_LDA(At, 1, 0); PG8_STAGE(PG8_SA(0, 1), a2 + hA2, oA2, qA2);
;             PG8_WAIT_V(8); PG8_WAIT_L(0); PG8_BAR; PG8_MMA(0, 0, At, B0); PG8_MMA(0, 1, At, B1); PG8_BAR; PG8_SCHED;
	s_setprio 1
	s_waitcnt lgkmcnt(0)
	v_mfma_f32_16x16x32_bf16 v[62:65], v[140:143], v[202:205], v[62:65]
	v_mfma_f32_16x16x32_bf16 v[58:61], v[154:157], v[202:205], v[58:61]
	v_mfma_f32_16x16x32_bf16 v[46:49], v[140:143], v[210:213], v[46:49]
	v_mfma_f32_16x16x32_bf16 v[42:45], v[154:157], v[210:213], v[42:45]
	v_mfma_f32_16x16x32_bf16 v[30:33], v[140:143], v[218:221], v[30:33]
	v_mfma_f32_16x16x32_bf16 v[26:29], v[154:157], v[218:221], v[26:29]
	v_mfma_f32_16x16x32_bf16 v[14:17], v[140:143], v[226:229], v[14:17]
	v_mfma_f32_16x16x32_bf16 v[10:13], v[154:157], v[226:229], v[10:13]
	v_mfma_f32_16x16x32_bf16 v[62:65], v[150:153], v[206:209], v[62:65]
	v_mfma_f32_16x16x32_bf16 v[58:61], v[158:161], v[206:209], v[58:61]
	v_mfma_f32_16x16x32_bf16 v[46:49], v[150:153], v[214:217], v[46:49]
	v_mfma_f32_16x16x32_bf16 v[42:45], v[158:161], v[214:217], v[42:45]
	v_mfma_f32_16x16x32_bf16 v[30:33], v[150:153], v[222:225], v[30:33]
	v_mfma_f32_16x16x32_bf16 v[26:29], v[158:161], v[222:225], v[26:29]
	v_mfma_f32_16x16x32_bf16 v[14:17], v[150:153], v[230:233], v[14:17]
	v_mfma_f32_16x16x32_bf16 v[10:13], v[158:161], v[230:233], v[10:13]
	s_setprio 0
	s_setprio 1
	v_mfma_f32_16x16x32_bf16 v[54:57], v[186:189], v[202:205], v[54:57]
	v_mfma_f32_16x16x32_bf16 v[50:53], v[194:197], v[202:205], v[50:53]
	v_mfma_f32_16x16x32_bf16 v[38:41], v[186:189], v[210:213], v[38:41]
	v_mfma_f32_16x16x32_bf16 v[34:37], v[194:197], v[210:213], v[34:37]
	v_mfma_f32_16x16x32_bf16 v[22:25], v[186:189], v[218:221], v[22:25]
	v_mfma_f32_16x16x32_bf16 v[18:21], v[194:197], v[218:221], v[18:21]
	v_mfma_f32_16x16x32_bf16 v[6:9], v[186:189], v[226:229], v[6:9]
	v_mfma_f32_16x16x32_bf16 v[2:5], v[194:197], v[226:229], v[2:5]
	v_mfma_f32_16x16x32_bf16 v[54:57], v[190:193], v[206:209], v[54:57]
	v_mfma_f32_16x16x32_bf16 v[50:53], v[198:201], v[206:209], v[50:53]
	v_mfma_f32_16x16x32_bf16 v[38:41], v[190:193], v[214:217], v[38:41]
	v_mfma_f32_16x16x32_bf16 v[34:37], v[198:201], v[214:217], v[34:37]
	v_mfma_f32_16x16x32_bf16 v[22:25], v[190:193], v[222:225], v[22:25]
	v_mfma_f32_16x16x32_bf16 v[18:21], v[198:201], v[222:225], v[18:21]
	v_mfma_f32_16x16x32_bf16 v[6:9], v[190:193], v[230:233], v[6:9]
	v_mfma_f32_16x16x32_bf16 v[2:5], v[198:201], v[230:233], v[2:5]
	s_setprio 0
	s_barrier
	s_add_i32 s10, 0, 0x18000
	s_add_i32 s11, 0, 0x1c000
	ds_read_b128 v[140:143], v133 offset:32768
	ds_read_b128 v[150:153], v133 offset:33792
	ds_read_b128 v[154:157], v133 offset:34816
	ds_read_b128 v[158:161], v133 offset:35840
	ds_read_b128 v[186:189], v133 offset:49152
	ds_read_b128 v[190:193], v133 offset:50176
	ds_read_b128 v[194:197], v133 offset:51200
	ds_read_b128 v[198:201], v133 offset:52224
	s_add_u32 s6, vcc_lo, s58
	s_addc_u32 s7, vcc_hi, s59
	s_mov_b32 m0, s91
	ds_read_b128 v[202:205], v184 offset:32768
	ds_read_b128 v[206:209], v184 offset:33792
	ds_read_b128 v[210:213], v184 offset:34816
	ds_read_b128 v[214:217], v184 offset:35840
	ds_read_b128 v[218:221], v184 offset:36864
	ds_read_b128 v[222:225], v184 offset:37888
	ds_read_b128 v[226:229], v184 offset:38912
	ds_read_b128 v[230:233], v184 offset:39936
	global_load_lds_dwordx4 v136, s[6:7]
	s_add_u32 s6, s6, s64
	s_addc_u32 s7, s7, s65
	s_mov_b32 m0, s93
	s_nop 0
	global_load_lds_dwordx4 v136, s[6:7]
	s_waitcnt vmcnt(8)
	s_waitcnt lgkmcnt(0)
	s_barrier
	s_setprio 1
	s_waitcnt lgkmcnt(0)
	v_mfma_f32_16x16x32_bf16 v[126:129], v[140:143], v[202:205], v[126:129]
	v_mfma_f32_16x16x32_bf16 v[122:125], v[154:157], v[202:205], v[122:125]
	v_mfma_f32_16x16x32_bf16 v[110:113], v[140:143], v[210:213], v[110:113]
	v_mfma_f32_16x16x32_bf16 v[106:109], v[154:157], v[210:213], v[106:109]
	v_mfma_f32_16x16x32_bf16 v[94:97], v[140:143], v[218:221], v[94:97]
	v_mfma_f32_16x16x32_bf16 v[90:93], v[154:157], v[218:221], v[90:93]
	v_mfma_f32_16x16x32_bf16 v[78:81], v[140:143], v[226:229], v[78:81]
	v_mfma_f32_16x16x32_bf16 v[74:77], v[154:157], v[226:229], v[74:77]
	v_mfma_f32_16x16x32_bf16 v[126:129], v[150:153], v[206:209], v[126:129]
	v_mfma_f32_16x16x32_bf16 v[122:125], v[158:161], v[206:209], v[122:125]
	v_mfma_f32_16x16x32_bf16 v[110:113], v[150:153], v[214:217], v[110:113]
	v_mfma_f32_16x16x32_bf16 v[106:109], v[158:161], v[214:217], v[106:109]
	v_mfma_f32_16x16x32_bf16 v[94:97], v[150:153], v[222:225], v[94:97]
	v_mfma_f32_16x16x32_bf16 v[90:93], v[158:161], v[222:225], v[90:93]
	v_mfma_f32_16x16x32_bf16 v[78:81], v[150:153], v[230:233], v[78:81]
	v_mfma_f32_16x16x32_bf16 v[74:77], v[158:161], v[230:233], v[74:77]
	s_setprio 0
	s_setprio 1
	v_mfma_f32_16x16x32_bf16 v[118:121], v[186:189], v[202:205], v[118:121]
	v_mfma_f32_16x16x32_bf16 v[114:117], v[194:197], v[202:205], v[114:117]
	v_mfma_f32_16x16x32_bf16 v[102:105], v[186:189], v[210:213], v[102:105]
	v_mfma_f32_16x16x32_bf16 v[98:101], v[194:197], v[210:213], v[98:101]
	v_mfma_f32_16x16x32_bf16 v[86:89], v[186:189], v[218:221], v[86:89]
	v_mfma_f32_16x16x32_bf16 v[82:85], v[194:197], v[218:221], v[82:85]
	v_mfma_f32_16x16x32_bf16 v[70:73], v[186:189], v[226:229], v[70:73]
	v_mfma_f32_16x16x32_bf16 v[66:69], v[194:197], v[226:229], v[66:69]
	v_mfma_f32_16x16x32_bf16 v[118:121], v[190:193], v[206:209], v[118:121]
	v_mfma_f32_16x16x32_bf16 v[114:117], v[198:201], v[206:209], v[114:117]
	v_mfma_f32_16x16x32_bf16 v[102:105], v[190:193], v[214:217], v[102:105]
	v_mfma_f32_16x16x32_bf16 v[98:101], v[198:201], v[214:217], v[98:101]
	v_mfma_f32_16x16x32_bf16 v[86:89], v[190:193], v[222:225], v[86:89]
	v_mfma_f32_16x16x32_bf16 v[82:85], v[198:201], v[222:225], v[82:85]
	v_mfma_f32_16x16x32_bf16 v[70:73], v[190:193], v[230:233], v[70:73]
	v_mfma_f32_16x16x32_bf16 v[66:69], v[198:201], v[230:233], v[66:69]
	s_setprio 0
	s_barrier
; #define PG8_STAGE(bufoff, gbase, off, q) do { \
;         __builtin_amdgcn_global_load_lds((const unsigned*)((const char*)(gbase) + (off)), (LAS unsigned*)(lds + (bufoff) + ldsw), 16, 0, 0); \
;         __builtin_amdgcn_global_load_lds((const unsigned*)((const char*)(gbase) + (q) + (off)), (LAS unsigned*)(lds + (bufoff) + ldsw + 8192), 16, 0, 0); } while (0)
; #define PG8_LDA(dst, b, h) do { _Pragma("unroll") for (int m = 0; m < 4; ++m) _Pragma("unroll") for (int k = 0; k < 2; ++k) dst[m][k] = *(const LAS bf16x8*)(lds + PG8_SA(b, h) + aoff + m * 2048 + k * 1024); } while (0)
; #define PG8_MMA(ai, bj, At, Bt) do { __builtin_amdgcn_s_setprio(1); _Pragma("unroll") for (int m = 0; m < 4; ++m) _Pragma("unroll") for (int n = 0; n < 2; ++n) _Pragma("unroll") for (int k = 0; k < 2; ++k) \
;         acc[ai][bj][m][n] = __builtin_amdgcn_mfma_f32_16x16x32_bf16(Bt[n][k], At[m][k], acc[ai][bj][m][n], 0, 0, 0); __builtin_amdgcn_s_setprio(0); } while (0)
; #define PG8_WAIT_V(n) asm volatile("s_waitcnt vmcnt(" #n ")" ::: "memory")
; #define PG8_WAIT_L(n) asm volatile("s_waitcnt lgkmcnt(" #n ")" ::: "memory")
; #define PG8_BAR __builtin_amdgcn_s_barrier()
; #define PG8_SCHED __builtin_amdgcn_sched_barrier(0)
; template <class Epi, class Sched>
; __device__ __forceinline__ void gemm_phase(LAS unsigned char* lds, const int tid, const Sched& S, const Epi& E) {
;     ...
;             PG8_LDA(At, 1, 1); PG8_STAGE(PG8_SB(1, 0), b3, oB2, qB2); PG8_STAGE(PG8_SB(1, 1), b3 + hB2, oB2, qB2); PG8_STAGE(PG8_SA(1, 0), a3, oA2, qA2);
;             PG8_WAIT_V(8); PG8_WAIT_L(0); PG8_BAR; PG8_MMA(1, 0, At, B0); PG8_MMA(1, 1, At, B1); PG8_BAR; PG8_SCHED;
;         }
	s_add_i32 s6, s10, s47
	s_add_i32 m0, s6, 0xffffff80
	ds_read_b128 v[202:205], v184 offset:49152
	ds_read_b128 v[206:209], v184 offset:50176
	ds_read_b128 v[210:213], v184 offset:51200
	ds_read_b128 v[214:217], v184 offset:52224
	ds_read_b128 v[218:221], v184 offset:53248
	ds_read_b128 v[222:225], v184 offset:54272
	ds_read_b128 v[226:229], v184 offset:55296
	ds_read_b128 v[230:233], v184 offset:56320
	global_load_lds_dwordx4 v0, s[28:29] offset:128
	s_add_i32 m0, s6, 0x1f80
	s_add_i32 s6, s11, s47
	s_ashr_i32 s100, s73, 31
	s_add_u32 s98, s28, s73
	s_addc_u32 s99, s29, s100
	global_load_lds_dwordx4 v0, s[98:99] offset:128
	s_add_i32 m0, s6, 0xffffff80
	s_nop 0
	s_ashr_i32 s101, s19, 31
	s_add_u32 s98, s28, s19
	s_addc_u32 s99, s29, s101
	global_load_lds_dwordx4 v0, s[98:99] offset:128
	s_add_i32 m0, s6, 0x1f80
	s_nop 0
	s_add_u32 s98, s98, s73
	s_addc_u32 s99, s99, s100
	global_load_lds_dwordx4 v0, s[98:99] offset:128
	s_add_i32 m0, s77, 0xffffff80
	s_nop 0
	global_load_lds_dwordx4 v136, vcc offset:128
	s_add_i32 m0, s88, 0xffffff80
	s_nop 0
	s_add_u32 s98, vcc_lo, s64
	s_addc_u32 s99, vcc_hi, s65
	global_load_lds_dwordx4 v136, s[98:99] offset:128
	s_waitcnt vmcnt(8)
	s_waitcnt lgkmcnt(0)
	s_barrier
	s_setprio 1
	s_waitcnt lgkmcnt(0)
	v_mfma_f32_16x16x32_bf16 v[62:65], v[140:143], v[202:205], v[62:65]
	v_mfma_f32_16x16x32_bf16 v[58:61], v[154:157], v[202:205], v[58:61]
	v_mfma_f32_16x16x32_bf16 v[46:49], v[140:143], v[210:213], v[46:49]
	v_mfma_f32_16x16x32_bf16 v[42:45], v[154:157], v[210:213], v[42:45]
	v_mfma_f32_16x16x32_bf16 v[30:33], v[140:143], v[218:221], v[30:33]
	v_mfma_f32_16x16x32_bf16 v[26:29], v[154:157], v[218:221], v[26:29]
	v_mfma_f32_16x16x32_bf16 v[14:17], v[140:143], v[226:229], v[14:17]
	v_mfma_f32_16x16x32_bf16 v[10:13], v[154:157], v[226:229], v[10:13]
	v_mfma_f32_16x16x32_bf16 v[62:65], v[150:153], v[206:209], v[62:65]
	v_mfma_f32_16x16x32_bf16 v[58:61], v[158:161], v[206:209], v[58:61]
	v_mfma_f32_16x16x32_bf16 v[46:49], v[150:153], v[214:217], v[46:49]
	v_mfma_f32_16x16x32_bf16 v[42:45], v[158:161], v[214:217], v[42:45]
	v_mfma_f32_16x16x32_bf16 v[30:33], v[150:153], v[222:225], v[30:33]
	v_mfma_f32_16x16x32_bf16 v[26:29], v[158:161], v[222:225], v[26:29]
	v_mfma_f32_16x16x32_bf16 v[14:17], v[150:153], v[230:233], v[14:17]
	v_mfma_f32_16x16x32_bf16 v[10:13], v[158:161], v[230:233], v[10:13]
	s_setprio 0
	s_setprio 1
	v_mfma_f32_16x16x32_bf16 v[54:57], v[186:189], v[202:205], v[54:57]
	v_mfma_f32_16x16x32_bf16 v[50:53], v[194:197], v[202:205], v[50:53]
	v_mfma_f32_16x16x32_bf16 v[38:41], v[186:189], v[210:213], v[38:41]
	v_mfma_f32_16x16x32_bf16 v[34:37], v[194:197], v[210:213], v[34:37]
	v_mfma_f32_16x16x32_bf16 v[22:25], v[186:189], v[218:221], v[22:25]
	v_mfma_f32_16x16x32_bf16 v[18:21], v[194:197], v[218:221], v[18:21]
	v_mfma_f32_16x16x32_bf16 v[6:9], v[186:189], v[226:229], v[6:9]
	v_mfma_f32_16x16x32_bf16 v[2:5], v[194:197], v[226:229], v[2:5]
	v_mfma_f32_16x16x32_bf16 v[54:57], v[190:193], v[206:209], v[54:57]
	v_mfma_f32_16x16x32_bf16 v[50:53], v[198:201], v[206:209], v[50:53]
	v_mfma_f32_16x16x32_bf16 v[38:41], v[190:193], v[214:217], v[38:41]
	v_mfma_f32_16x16x32_bf16 v[34:37], v[198:201], v[214:217], v[34:37]
	v_mfma_f32_16x16x32_bf16 v[22:25], v[190:193], v[222:225], v[22:25]
	v_mfma_f32_16x16x32_bf16 v[18:21], v[198:201], v[222:225], v[18:21]
	v_mfma_f32_16x16x32_bf16 v[6:9], v[190:193], v[230:233], v[6:9]
	v_mfma_f32_16x16x32_bf16 v[2:5], v[198:201], v[230:233], v[2:5]
	s_setprio 0
	s_barrier
	s_cmp_ge_i32 s20, s37
	s_cbranch_scc1 .LBB0_177
	s_mov_b32 s17, s20
	s_branch .LBB0_173

; #define PG8_STAGE(bufoff, gbase, off, q) do { \
;         __builtin_amdgcn_global_load_lds((const unsigned*)((const char*)(gbase) + (off)), (LAS unsigned*)(lds + (bufoff) + ldsw), 16, 0, 0); \
;         __builtin_amdgcn_global_load_lds((const unsigned*)((const char*)(gbase) + (q) + (off)), (LAS unsigned*)(lds + (bufoff) + ldsw + 8192), 16, 0, 0); } while (0)
; #define PG8_LDA(dst, b, h) do { _Pragma("unroll") for (int m = 0; m < 4; ++m) _Pragma("unroll") for (int k = 0; k < 2; ++k) dst[m][k] = *(const LAS bf16x8*)(lds + PG8_SA(b, h) + aoff + m * 2048 + k * 1024); } while (0)
; #define PG8_LDB(dst, b, h) do { _Pragma("unroll") for (int n = 0; n < 2; ++n) _Pragma("unroll") for (int k = 0; k < 2; ++k) dst[n][k] = *(const LAS bf16x8*)(lds + PG8_SB(b, h) + boff + n * 2048 + k * 1024); } while (0)
; #define PG8_MMA(ai, bj, At, Bt) do { __builtin_amdgcn_s_setprio(1); _Pragma("unroll") for (int m = 0; m < 4; ++m) _Pragma("unroll") for (int n = 0; n < 2; ++n) _Pragma("unroll") for (int k = 0; k < 2; ++k) \
;         acc[ai][bj][m][n] = __builtin_amdgcn_mfma_f32_16x16x32_bf16(Bt[n][k], At[m][k], acc[ai][bj][m][n], 0, 0, 0); __builtin_amdgcn_s_setprio(0); } while (0)
; template <class Epi, class Sched>
; __device__ __forceinline__ void gemm_phase(LAS unsigned char* lds, const int tid, const Sched& S, const Epi& E) {
;     ...
;             const bool last = (t == nt - 2);
;             const char* a1 = cA + (size_t)(t + 1) * kstep;
;             const char* a2 = last ? nA : cA + (size_t)(t + 2) * kstep; const char* b2 = last ? nB : cB + (size_t)(t + 2) * kstep;
;             const char* a3 = a2 + kstep; const char* b3 = b2 + kstep;
;             const unsigned oA2 = last ? noffA : offA, oB2 = last ? noffB : offB;
;             const int qA2 = last ? nqA : qA, qB2 = last ? nqB : qB, hA2 = last ? nhA : hA, hB2 = last ? nhB : hB;
;             PG8_LDB(B0, 0, 0); PG8_LDB(B1, 0, 1); PG8_SCHED; PG8_LDA(At, 0, 0); PG8_STAGE(PG8_SA(1, 1), a1 + hA, offA, qA);
;             PG8_WAIT_V(8); PG8_WAIT_L(0); PG8_BAR; PG8_MMA(0, 0, At, B0); PG8_MMA(0, 1, At, B1); PG8_BAR; PG8_SCHED;
;             PG8_LDA(At, 0, 1); PG8_STAGE(PG8_SB(0, 0), b2, oB2, qB2); PG8_STAGE(PG8_SB(0, 1), b2 + hB2, oB2, qB2); PG8_STAGE(PG8_SA(0, 0), a2, oA2, qA2);
;             PG8_WAIT_V(8); PG8_WAIT_L(0); PG8_BAR; PG8_MMA(1, 0, At, B0); PG8_MMA(1, 1, At, B1); PG8_BAR; PG8_SCHED;
.Lk0b_175:
	s_or_b32 vcc_lo, s17, 1
	s_mov_b32 vcc_hi, s21
	s_lshl_b64 s[10:11], vcc, 7
	s_add_u32 s17, s40, s6
	s_addc_u32 vcc_lo, s41, s7
	s_and_b64 s[6:7], exec, s[62:63]
	s_cselect_b32 vcc_hi, s82, vcc_lo
	s_cselect_b32 vcc_lo, s48, s17
	s_add_i32 s17, 0, 0x10000
	v_add_u32_e32 v133, s17, v147
	s_add_i32 s62, 0, 0x14000
	ds_read_b128 v[140:143], v133
	ds_read_b128 v[150:153], v133 offset:1024
	ds_read_b128 v[154:157], v133 offset:2048
	ds_read_b128 v[158:161], v133 offset:3072
	ds_read_b128 v[186:189], v133 offset:16384
	ds_read_b128 v[190:193], v133 offset:17408
	ds_read_b128 v[194:197], v133 offset:18432
	ds_read_b128 v[198:201], v133 offset:19456
	s_add_u32 s6, s68, s10
	s_addc_u32 s7, s16, s11
	s_add_i32 m0, s54, 0xc000
	ds_read_b128 v[202:205], v184
	ds_read_b128 v[206:209], v184 offset:1024
	ds_read_b128 v[210:213], v184 offset:2048
	ds_read_b128 v[214:217], v184 offset:3072
	ds_read_b128 v[218:221], v184 offset:4096
	ds_read_b128 v[222:225], v184 offset:5120
	ds_read_b128 v[226:229], v184 offset:6144
	ds_read_b128 v[230:233], v184 offset:7168
	global_load_lds_dwordx4 v134, s[6:7]
	s_add_u32 s6, s6, s66
	s_addc_u32 s7, s7, s67
	s_add_i32 m0, s54, 0xe000
	s_nop 0
	global_load_lds_dwordx4 v134, s[6:7]
	s_waitcnt vmcnt(24)
	s_waitcnt lgkmcnt(0)
	s_barrier
	s_setprio 1
	s_waitcnt lgkmcnt(0)
	v_mfma_f32_16x16x32_bf16 v[126:129], v[140:143], v[202:205], v[126:129]
	v_mfma_f32_16x16x32_bf16 v[122:125], v[154:157], v[202:205], v[122:125]
	v_mfma_f32_16x16x32_bf16 v[110:113], v[140:143], v[210:213], v[110:113]
	v_mfma_f32_16x16x32_bf16 v[106:109], v[154:157], v[210:213], v[106:109]
	v_mfma_f32_16x16x32_bf16 v[94:97], v[140:143], v[218:221], v[94:97]
	v_mfma_f32_16x16x32_bf16 v[90:93], v[154:157], v[218:221], v[90:93]
	v_mfma_f32_16x16x32_bf16 v[78:81], v[140:143], v[226:229], v[78:81]
	v_mfma_f32_16x16x32_bf16 v[74:77], v[154:157], v[226:229], v[74:77]
	v_mfma_f32_16x16x32_bf16 v[126:129], v[150:153], v[206:209], v[126:129]
	v_mfma_f32_16x16x32_bf16 v[122:125], v[158:161], v[206:209], v[122:125]
	v_mfma_f32_16x16x32_bf16 v[110:113], v[150:153], v[214:217], v[110:113]
	v_mfma_f32_16x16x32_bf16 v[106:109], v[158:161], v[214:217], v[106:109]
	v_mfma_f32_16x16x32_bf16 v[94:97], v[150:153], v[222:225], v[94:97]
	v_mfma_f32_16x16x32_bf16 v[90:93], v[158:161], v[222:225], v[90:93]
	v_mfma_f32_16x16x32_bf16 v[78:81], v[150:153], v[230:233], v[78:81]
	v_mfma_f32_16x16x32_bf16 v[74:77], v[158:161], v[230:233], v[74:77]
	s_setprio 0
	s_setprio 1
	v_mfma_f32_16x16x32_bf16 v[118:121], v[186:189], v[202:205], v[118:121]
	v_mfma_f32_16x16x32_bf16 v[114:117], v[194:197], v[202:205], v[114:117]
	v_mfma_f32_16x16x32_bf16 v[102:105], v[186:189], v[210:213], v[102:105]
	v_mfma_f32_16x16x32_bf16 v[98:101], v[194:197], v[210:213], v[98:101]
	v_mfma_f32_16x16x32_bf16 v[86:89], v[186:189], v[218:221], v[86:89]
	v_mfma_f32_16x16x32_bf16 v[82:85], v[194:197], v[218:221], v[82:85]
	v_mfma_f32_16x16x32_bf16 v[70:73], v[186:189], v[226:229], v[70:73]
	v_mfma_f32_16x16x32_bf16 v[66:69], v[194:197], v[226:229], v[66:69]
	v_mfma_f32_16x16x32_bf16 v[118:121], v[190:193], v[206:209], v[118:121]
	v_mfma_f32_16x16x32_bf16 v[114:117], v[198:201], v[206:209], v[114:117]
	v_mfma_f32_16x16x32_bf16 v[102:105], v[190:193], v[214:217], v[102:105]
	v_mfma_f32_16x16x32_bf16 v[98:101], v[198:201], v[214:217], v[98:101]
	v_mfma_f32_16x16x32_bf16 v[86:89], v[190:193], v[222:225], v[86:89]
	v_mfma_f32_16x16x32_bf16 v[82:85], v[198:201], v[222:225], v[82:85]
	v_mfma_f32_16x16x32_bf16 v[70:73], v[190:193], v[230:233], v[70:73]
	v_mfma_f32_16x16x32_bf16 v[66:69], v[198:201], v[230:233], v[66:69]
	s_setprio 0
	s_barrier
	s_add_i32 s10, s17, s47
	s_ashr_i32 s11, s73, 31
	s_mov_b32 m0, s10
	s_add_u32 s6, s28, s73
	ds_read_b128 v[202:205], v184 offset:16384
	ds_read_b128 v[206:209], v184 offset:17408
	ds_read_b128 v[210:213], v184 offset:18432
	ds_read_b128 v[214:217], v184 offset:19456
	ds_read_b128 v[218:221], v184 offset:20480
	ds_read_b128 v[222:225], v184 offset:21504
	ds_read_b128 v[226:229], v184 offset:22528
	ds_read_b128 v[230:233], v184 offset:23552
	global_load_lds_dwordx4 v0, s[28:29]
	s_addc_u32 s7, s29, s11
	s_add_i32 m0, s10, 0x2000
	s_nop 0
	global_load_lds_dwordx4 v0, s[6:7]
	s_ashr_i32 s7, s19, 31
	s_add_u32 s6, s28, s19
	s_addc_u32 s7, s29, s7
	s_add_i32 s10, s62, s47
	s_mov_b32 m0, s10
	s_nop 0
	global_load_lds_dwordx4 v0, s[6:7]
	s_add_u32 s6, s6, s73
	s_addc_u32 s7, s7, s11
	s_add_i32 m0, s10, 0x2000
	s_nop 0
	global_load_lds_dwordx4 v0, s[6:7]
	s_add_u32 s6, vcc_lo, s64
	s_mov_b32 m0, s54
	s_addc_u32 s7, vcc_hi, s65
	global_load_lds_dwordx4 v136, vcc
	s_mov_b32 m0, s55
	s_nop 0
	global_load_lds_dwordx4 v136, s[6:7]
	s_waitcnt vmcnt(24)
	s_waitcnt lgkmcnt(0)
	s_barrier
; #define PG8_STAGE(bufoff, gbase, off, q) do { \
;         __builtin_amdgcn_global_load_lds((const unsigned*)((const char*)(gbase) + (off)), (LAS unsigned*)(lds + (bufoff) + ldsw), 16, 0, 0); \
;         __builtin_amdgcn_global_load_lds((const unsigned*)((const char*)(gbase) + (q) + (off)), (LAS unsigned*)(lds + (bufoff) + ldsw + 8192), 16, 0, 0); } while (0)
; #define PG8_LDA(dst, b, h) do { _Pragma("unroll") for (int m = 0; m < 4; ++m) _Pragma("unroll") for (int k = 0; k < 2; ++k) dst[m][k] = *(const LAS bf16x8*)(lds + PG8_SA(b, h) + aoff + m * 2048 + k * 1024); } while (0)
; #define PG8_LDB(dst, b, h) do { _Pragma("unroll") for (int n = 0; n < 2; ++n) _Pragma("unroll") for (int k = 0; k < 2; ++k) dst[n][k] = *(const LAS bf16x8*)(lds + PG8_SB(b, h) + boff + n * 2048 + k * 1024); } while (0)
; #define PG8_MMA(ai, bj, At, Bt) do { __builtin_amdgcn_s_setprio(1); _Pragma("unroll") for (int m = 0; m < 4; ++m) _Pragma("unroll") for (int n = 0; n < 2; ++n) _Pragma("unroll") for (int k = 0; k < 2; ++k) \
;         acc[ai][bj][m][n] = __builtin_amdgcn_mfma_f32_16x16x32_bf16(Bt[n][k], At[m][k], acc[ai][bj][m][n], 0, 0, 0); __builtin_amdgcn_s_setprio(0); } while (0)
; #define PG8_WAIT_V(n) asm volatile("s_waitcnt vmcnt(" #n ")" ::: "memory")
; #define PG8_WAIT_L(n) asm volatile("s_waitcnt lgkmcnt(" #n ")" ::: "memory")
; #define PG8_BAR __builtin_amdgcn_s_barrier()
; #define PG8_SCHED __builtin_amdgcn_sched_barrier(0)
; template <class Epi, class Sched>
; __device__ __forceinline__ void gemm_phase(LAS unsigned char* lds, const int tid, const Sched& S, const Epi& E) {
;     ...
;             PG8_WAIT_V(8); PG8_WAIT_L(0); PG8_BAR; PG8_MMA(1, 0, At, B0); PG8_MMA(1, 1, At, B1); PG8_BAR; PG8_SCHED;
;             PG8_LDB(B0, 1, 0); PG8_LDB(B1, 1, 1); PG8_SCHED; PG8_LDA(At, 1, 0); PG8_STAGE(PG8_SA(0, 1), a2 + hA2, oA2, qA2);
;             PG8_WAIT_V(8); PG8_WAIT_L(0); PG8_BAR; PG8_MMA(0, 0, At, B0); PG8_MMA(0, 1, At, B1); PG8_BAR; PG8_SCHED;
	s_setprio 1
	s_waitcnt lgkmcnt(0)
	v_mfma_f32_16x16x32_bf16 v[62:65], v[140:143], v[202:205], v[62:65]
	v_mfma_f32_16x16x32_bf16 v[58:61], v[154:157], v[202:205], v[58:61]
	v_mfma_f32_16x16x32_bf16 v[46:49], v[140:143], v[210:213], v[46:49]
	v_mfma_f32_16x16x32_bf16 v[42:45], v[154:157], v[210:213], v[42:45]
	v_mfma_f32_16x16x32_bf16 v[30:33], v[140:143], v[218:221], v[30:33]
	v_mfma_f32_16x16x32_bf16 v[26:29], v[154:157], v[218:221], v[26:29]
	v_mfma_f32_16x16x32_bf16 v[14:17], v[140:143], v[226:229], v[14:17]
	v_mfma_f32_16x16x32_bf16 v[10:13], v[154:157], v[226:229], v[10:13]
	v_mfma_f32_16x16x32_bf16 v[62:65], v[150:153], v[206:209], v[62:65]
	v_mfma_f32_16x16x32_bf16 v[58:61], v[158:161], v[206:209], v[58:61]
	v_mfma_f32_16x16x32_bf16 v[46:49], v[150:153], v[214:217], v[46:49]
	v_mfma_f32_16x16x32_bf16 v[42:45], v[158:161], v[214:217], v[42:45]
	v_mfma_f32_16x16x32_bf16 v[30:33], v[150:153], v[222:225], v[30:33]
	v_mfma_f32_16x16x32_bf16 v[26:29], v[158:161], v[222:225], v[26:29]
	v_mfma_f32_16x16x32_bf16 v[14:17], v[150:153], v[230:233], v[14:17]
	v_mfma_f32_16x16x32_bf16 v[10:13], v[158:161], v[230:233], v[10:13]
	s_setprio 0
	s_setprio 1
	v_mfma_f32_16x16x32_bf16 v[54:57], v[186:189], v[202:205], v[54:57]
	v_mfma_f32_16x16x32_bf16 v[50:53], v[194:197], v[202:205], v[50:53]
	v_mfma_f32_16x16x32_bf16 v[38:41], v[186:189], v[210:213], v[38:41]
	v_mfma_f32_16x16x32_bf16 v[34:37], v[194:197], v[210:213], v[34:37]
	v_mfma_f32_16x16x32_bf16 v[22:25], v[186:189], v[218:221], v[22:25]
	v_mfma_f32_16x16x32_bf16 v[18:21], v[194:197], v[218:221], v[18:21]
	v_mfma_f32_16x16x32_bf16 v[6:9], v[186:189], v[226:229], v[6:9]
	v_mfma_f32_16x16x32_bf16 v[2:5], v[194:197], v[226:229], v[2:5]
	v_mfma_f32_16x16x32_bf16 v[54:57], v[190:193], v[206:209], v[54:57]
	v_mfma_f32_16x16x32_bf16 v[50:53], v[198:201], v[206:209], v[50:53]
	v_mfma_f32_16x16x32_bf16 v[38:41], v[190:193], v[214:217], v[38:41]
	v_mfma_f32_16x16x32_bf16 v[34:37], v[198:201], v[214:217], v[34:37]
	v_mfma_f32_16x16x32_bf16 v[22:25], v[190:193], v[222:225], v[22:25]
	v_mfma_f32_16x16x32_bf16 v[18:21], v[198:201], v[222:225], v[18:21]
	v_mfma_f32_16x16x32_bf16 v[6:9], v[190:193], v[230:233], v[6:9]
	v_mfma_f32_16x16x32_bf16 v[2:5], v[198:201], v[230:233], v[2:5]
	s_setprio 0
	s_barrier
	s_add_i32 s10, 0, 0x18000
	s_add_i32 s11, 0, 0x1c000
	ds_read_b128 v[140:143], v133 offset:32768
	ds_read_b128 v[150:153], v133 offset:33792
	ds_read_b128 v[154:157], v133 offset:34816
	ds_read_b128 v[158:161], v133 offset:35840
	ds_read_b128 v[186:189], v133 offset:49152
	ds_read_b128 v[190:193], v133 offset:50176
	ds_read_b128 v[194:197], v133 offset:51200
	ds_read_b128 v[198:201], v133 offset:52224
	s_add_u32 s6, vcc_lo, s58
	s_addc_u32 s7, vcc_hi, s59
	s_mov_b32 m0, s91
	ds_read_b128 v[202:205], v184 offset:32768
	ds_read_b128 v[206:209], v184 offset:33792
	ds_read_b128 v[210:213], v184 offset:34816
	ds_read_b128 v[214:217], v184 offset:35840
	ds_read_b128 v[218:221], v184 offset:36864
	ds_read_b128 v[222:225], v184 offset:37888
	ds_read_b128 v[226:229], v184 offset:38912
	ds_read_b128 v[230:233], v184 offset:39936
	global_load_lds_dwordx4 v136, s[6:7]
	s_add_u32 s6, s6, s64
	s_addc_u32 s7, s7, s65
	s_mov_b32 m0, s93
	s_nop 0
	global_load_lds_dwordx4 v136, s[6:7]
	s_waitcnt vmcnt(8)
	s_waitcnt lgkmcnt(0)
	s_barrier
	s_setprio 1
	s_waitcnt lgkmcnt(0)
	v_mfma_f32_16x16x32_bf16 v[126:129], v[140:143], v[202:205], v[126:129]
	v_mfma_f32_16x16x32_bf16 v[122:125], v[154:157], v[202:205], v[122:125]
	v_mfma_f32_16x16x32_bf16 v[110:113], v[140:143], v[210:213], v[110:113]
	v_mfma_f32_16x16x32_bf16 v[106:109], v[154:157], v[210:213], v[106:109]
	v_mfma_f32_16x16x32_bf16 v[94:97], v[140:143], v[218:221], v[94:97]
	v_mfma_f32_16x16x32_bf16 v[90:93], v[154:157], v[218:221], v[90:93]
	v_mfma_f32_16x16x32_bf16 v[78:81], v[140:143], v[226:229], v[78:81]
	v_mfma_f32_16x16x32_bf16 v[74:77], v[154:157], v[226:229], v[74:77]
	v_mfma_f32_16x16x32_bf16 v[126:129], v[150:153], v[206:209], v[126:129]
	v_mfma_f32_16x16x32_bf16 v[122:125], v[158:161], v[206:209], v[122:125]
	v_mfma_f32_16x16x32_bf16 v[110:113], v[150:153], v[214:217], v[110:113]
	v_mfma_f32_16x16x32_bf16 v[106:109], v[158:161], v[214:217], v[106:109]
	v_mfma_f32_16x16x32_bf16 v[94:97], v[150:153], v[222:225], v[94:97]
	v_mfma_f32_16x16x32_bf16 v[90:93], v[158:161], v[222:225], v[90:93]
	v_mfma_f32_16x16x32_bf16 v[78:81], v[150:153], v[230:233], v[78:81]
	v_mfma_f32_16x16x32_bf16 v[74:77], v[158:161], v[230:233], v[74:77]
	s_setprio 0
	s_setprio 1
	v_mfma_f32_16x16x32_bf16 v[118:121], v[186:189], v[202:205], v[118:121]
	v_mfma_f32_16x16x32_bf16 v[114:117], v[194:197], v[202:205], v[114:117]
	v_mfma_f32_16x16x32_bf16 v[102:105], v[186:189], v[210:213], v[102:105]
	v_mfma_f32_16x16x32_bf16 v[98:101], v[194:197], v[210:213], v[98:101]
	v_mfma_f32_16x16x32_bf16 v[86:89], v[186:189], v[218:221], v[86:89]
	v_mfma_f32_16x16x32_bf16 v[82:85], v[194:197], v[218:221], v[82:85]
	v_mfma_f32_16x16x32_bf16 v[70:73], v[186:189], v[226:229], v[70:73]
	v_mfma_f32_16x16x32_bf16 v[66:69], v[194:197], v[226:229], v[66:69]
	v_mfma_f32_16x16x32_bf16 v[118:121], v[190:193], v[206:209], v[118:121]
	v_mfma_f32_16x16x32_bf16 v[114:117], v[198:201], v[206:209], v[114:117]
	v_mfma_f32_16x16x32_bf16 v[102:105], v[190:193], v[214:217], v[102:105]
	v_mfma_f32_16x16x32_bf16 v[98:101], v[198:201], v[214:217], v[98:101]
	v_mfma_f32_16x16x32_bf16 v[86:89], v[190:193], v[222:225], v[86:89]
	v_mfma_f32_16x16x32_bf16 v[82:85], v[198:201], v[222:225], v[82:85]
	v_mfma_f32_16x16x32_bf16 v[70:73], v[190:193], v[230:233], v[70:73]
	v_mfma_f32_16x16x32_bf16 v[66:69], v[198:201], v[230:233], v[66:69]
	s_setprio 0
	s_barrier
; #define PG8_STAGE(bufoff, gbase, off, q) do { \
;         __builtin_amdgcn_global_load_lds((const unsigned*)((const char*)(gbase) + (off)), (LAS unsigned*)(lds + (bufoff) + ldsw), 16, 0, 0); \
;         __builtin_amdgcn_global_load_lds((const unsigned*)((const char*)(gbase) + (q) + (off)), (LAS unsigned*)(lds + (bufoff) + ldsw + 8192), 16, 0, 0); } while (0)
; #define PG8_LDA(dst, b, h) do { _Pragma("unroll") for (int m = 0; m < 4; ++m) _Pragma("unroll") for (int k = 0; k < 2; ++k) dst[m][k] = *(const LAS bf16x8*)(lds + PG8_SA(b, h) + aoff + m * 2048 + k * 1024); } while (0)
; #define PG8_MMA(ai, bj, At, Bt) do { __builtin_amdgcn_s_setprio(1); _Pragma("unroll") for (int m = 0; m < 4; ++m) _Pragma("unroll") for (int n = 0; n < 2; ++n) _Pragma("unroll") for (int k = 0; k < 2; ++k) \
;         acc[ai][bj][m][n] = __builtin_amdgcn_mfma_f32_16x16x32_bf16(Bt[n][k], At[m][k], acc[ai][bj][m][n], 0, 0, 0); __builtin_amdgcn_s_setprio(0); } while (0)
; #define PG8_WAIT_V(n) asm volatile("s_waitcnt vmcnt(" #n ")" ::: "memory")
; #define PG8_WAIT_L(n) asm volatile("s_waitcnt lgkmcnt(" #n ")" ::: "memory")
; #define PG8_BAR __builtin_amdgcn_s_barrier()
; #define PG8_SCHED __builtin_amdgcn_sched_barrier(0)
; template <class Epi, class Sched>
; __device__ __forceinline__ void gemm_phase(LAS unsigned char* lds, const int tid, const Sched& S, const Epi& E) {
;     ...
;             PG8_LDA(At, 1, 1); PG8_STAGE(PG8_SB(1, 0), b3, oB2, qB2); PG8_STAGE(PG8_SB(1, 1), b3 + hB2, oB2, qB2); PG8_STAGE(PG8_SA(1, 0), a3, oA2, qA2);
;             PG8_WAIT_V(8); PG8_WAIT_L(0); PG8_BAR; PG8_MMA(1, 0, At, B0); PG8_MMA(1, 1, At, B1); PG8_BAR; PG8_SCHED;
;         }
	s_add_i32 s6, s10, s47
	s_add_i32 m0, s6, 0xffffff80
	ds_read_b128 v[202:205], v184 offset:49152
	ds_read_b128 v[206:209], v184 offset:50176
	ds_read_b128 v[210:213], v184 offset:51200
	ds_read_b128 v[214:217], v184 offset:52224
	ds_read_b128 v[218:221], v184 offset:53248
	ds_read_b128 v[222:225], v184 offset:54272
	ds_read_b128 v[226:229], v184 offset:55296
	ds_read_b128 v[230:233], v184 offset:56320
	global_load_lds_dwordx4 v0, s[28:29] offset:128
	s_add_i32 m0, s6, 0x1f80
	s_add_i32 s6, s11, s47
	s_ashr_i32 s100, s73, 31
	s_add_u32 s98, s28, s73
	s_addc_u32 s99, s29, s100
	global_load_lds_dwordx4 v0, s[98:99] offset:128
	s_add_i32 m0, s6, 0xffffff80
	s_nop 0
	s_ashr_i32 s101, s19, 31
	s_add_u32 s98, s28, s19
	s_addc_u32 s99, s29, s101
	global_load_lds_dwordx4 v0, s[98:99] offset:128
	s_add_i32 m0, s6, 0x1f80
	s_nop 0
	s_add_u32 s98, s98, s73
	s_addc_u32 s99, s99, s100
	global_load_lds_dwordx4 v0, s[98:99] offset:128
	s_add_i32 m0, s77, 0xffffff80
	s_nop 0
	global_load_lds_dwordx4 v136, vcc offset:128
	s_add_i32 m0, s88, 0xffffff80
	s_nop 0
	s_add_u32 s98, vcc_lo, s64
	s_addc_u32 s99, vcc_hi, s65
	global_load_lds_dwordx4 v136, s[98:99] offset:128
	s_waitcnt vmcnt(8)
	s_waitcnt lgkmcnt(0)
	s_barrier
	s_setprio 1
	s_waitcnt lgkmcnt(0)
	v_mfma_f32_16x16x32_bf16 v[62:65], v[140:143], v[202:205], v[62:65]
	v_mfma_f32_16x16x32_bf16 v[58:61], v[154:157], v[202:205], v[58:61]
	v_mfma_f32_16x16x32_bf16 v[46:49], v[140:143], v[210:213], v[46:49]
	v_mfma_f32_16x16x32_bf16 v[42:45], v[154:157], v[210:213], v[42:45]
	v_mfma_f32_16x16x32_bf16 v[30:33], v[140:143], v[218:221], v[30:33]
	v_mfma_f32_16x16x32_bf16 v[26:29], v[154:157], v[218:221], v[26:29]
	v_mfma_f32_16x16x32_bf16 v[14:17], v[140:143], v[226:229], v[14:17]
	v_mfma_f32_16x16x32_bf16 v[10:13], v[154:157], v[226:229], v[10:13]
	v_mfma_f32_16x16x32_bf16 v[62:65], v[150:153], v[206:209], v[62:65]
	v_mfma_f32_16x16x32_bf16 v[58:61], v[158:161], v[206:209], v[58:61]
	v_mfma_f32_16x16x32_bf16 v[46:49], v[150:153], v[214:217], v[46:49]
	v_mfma_f32_16x16x32_bf16 v[42:45], v[158:161], v[214:217], v[42:45]
	v_mfma_f32_16x16x32_bf16 v[30:33], v[150:153], v[222:225], v[30:33]
	v_mfma_f32_16x16x32_bf16 v[26:29], v[158:161], v[222:225], v[26:29]
	v_mfma_f32_16x16x32_bf16 v[14:17], v[150:153], v[230:233], v[14:17]
	v_mfma_f32_16x16x32_bf16 v[10:13], v[158:161], v[230:233], v[10:13]
	s_setprio 0
	s_setprio 1
	v_mfma_f32_16x16x32_bf16 v[54:57], v[186:189], v[202:205], v[54:57]
	v_mfma_f32_16x16x32_bf16 v[50:53], v[194:197], v[202:205], v[50:53]
	v_mfma_f32_16x16x32_bf16 v[38:41], v[186:189], v[210:213], v[38:41]
	v_mfma_f32_16x16x32_bf16 v[34:37], v[194:197], v[210:213], v[34:37]
	v_mfma_f32_16x16x32_bf16 v[22:25], v[186:189], v[218:221], v[22:25]
	v_mfma_f32_16x16x32_bf16 v[18:21], v[194:197], v[218:221], v[18:21]
	v_mfma_f32_16x16x32_bf16 v[6:9], v[186:189], v[226:229], v[6:9]
	v_mfma_f32_16x16x32_bf16 v[2:5], v[194:197], v[226:229], v[2:5]
	v_mfma_f32_16x16x32_bf16 v[54:57], v[190:193], v[206:209], v[54:57]
	v_mfma_f32_16x16x32_bf16 v[50:53], v[198:201], v[206:209], v[50:53]
	v_mfma_f32_16x16x32_bf16 v[38:41], v[190:193], v[214:217], v[38:41]
	v_mfma_f32_16x16x32_bf16 v[34:37], v[198:201], v[214:217], v[34:37]
	v_mfma_f32_16x16x32_bf16 v[22:25], v[190:193], v[222:225], v[22:25]
	v_mfma_f32_16x16x32_bf16 v[18:21], v[198:201], v[222:225], v[18:21]
	v_mfma_f32_16x16x32_bf16 v[6:9], v[190:193], v[230:233], v[6:9]
	v_mfma_f32_16x16x32_bf16 v[2:5], v[198:201], v[230:233], v[2:5]
	s_setprio 0
	s_barrier
	s_cmp_ge_i32 s20, s37
	s_cbranch_scc1 .LBB0_177
	s_mov_b32 s17, s20
	s_branch .LBB0_173
